# v66 + one 4-byte s_nop after P4: later GEMM loops back at the baseline's mod-8 byte phase (code placement, section 9.3)
# speedup vs baseline: 1.0096x; 1.0096x over previous
; #define LAS __attribute__((address_space(3)))
; __device__ __forceinline__ float sigmoidf_(float x) { return __builtin_amdgcn_rcpf(1.0f + __expf(-x)); }
; __device__ __forceinline__ void hg_pass1(Frame& F) {
;     LAS unsigned char* L = F.lds;
;     LAS bf16* QT = (LAS bf16*)(L); LAS bf16* KT = (LAS bf16*)(L + 17408); LAS bf16* KET = (LAS bf16*)(L + 34816); LAS bf16* VT = (LAS bf16*)(L + 53248); LAS bf16* PP = (LAS bf16*)(L + 71680);
;     LAS float* SEG = (LAS float*)(L + 80896);
;     const bf16* ZH = (const bf16*)(F.ws + WS_ZH);
;     bf16* OI = (bf16*)(F.ws + WS_OI); bf16* UT = (bf16*)(F.ws + WS_UT); bf16* Q0 = (bf16*)(F.ws + WS_Q0); float* ADEC = (float*)(F.ws + WS_ADEC);
;     const float* hglb = F.in[I_HGLB];
;     const int tid = F.tid, d = tid & 127, seg = tid >> 7, w = F.wave, lane = F.lane, r = lane & 31, hh = lane >> 5;
;     bf16 rq[16], rf[16], ri[16];
;     ...
;     if ((int)blockIdx.x < HGU) HG1_LOAD((int)blockIdx.x);
;     for (int u = blockIdx.x; u < HGU; u += F.G) {
;         int h, row0, nvalid; hg_decode(u, h, row0, nvalid);
;         const int hd = h * 128 + d;
;         const float lb = sigmoidf_(hglb[hd] - hglb[2048 + hd]);
.LBB0_480:
	s_add_u32 s4, s90, 0x8300000
	s_addc_u32 s5, s91, 0
	v_writelane_b32 v240, s4, 19
	v_cndmask_b32_e64 v2, 0, 1, s[0:1]
	v_lshlrev_b32_e32 v153, 4, v162
	v_writelane_b32 v240, s5, 20
	s_add_u32 s4, s90, 0x20d00000
	s_addc_u32 s5, s91, 0
	v_writelane_b32 v240, s4, 21
	s_andn2_b64 vcc, exec, s[0:1]
	s_nop 0
	v_writelane_b32 v240, s5, 22
	v_cmp_ne_u32_e64 s[4:5], 1, v2
	s_nop 1
	v_writelane_b32 v240, s4, 23
	s_nop 1
	v_writelane_b32 v240, s5, 24
	v_writelane_b32 v240, s8, 25
	v_writelane_b32 v240, s9, 26
	v_writelane_b32 v240, s76, 27
	s_nop 1
	v_writelane_b32 v240, s77, 28
	v_writelane_b32 v240, s82, 29
	s_nop 1
	v_writelane_b32 v240, s83, 30
	v_writelane_b32 v240, s80, 31
	s_nop 1
	v_writelane_b32 v240, s81, 32
	v_writelane_b32 v240, s79, 33
	s_cbranch_vccnz .LBB0_524
	v_writelane_b32 v240, s71, 34
	v_writelane_b32 v240, s84, 35
	s_add_i32 s0, 0, 0x13c00
	v_lshlrev_b32_e32 v20, 2, v18
	v_writelane_b32 v240, s85, 36
	v_writelane_b32 v240, s78, 37
	v_lshl_add_u32 v32, v0, 2, s0
	v_add_u32_e32 v33, s0, v20
	s_movk_i32 s0, 0x80
	v_writelane_b32 v240, s94, 38
	v_cmp_gt_u32_e64 s[12:13], s0, v0
	s_movk_i32 s0, 0xff
	v_writelane_b32 v240, s95, 39
	v_cmp_lt_u32_e64 s[14:15], s0, v0
	s_movk_i32 s0, 0x17f
	s_cmpk_lt_u32 s86, 0x100
	v_writelane_b32 v240, s74, 40
	v_cmp_lt_u32_e64 s[16:17], s0, v0
	s_cselect_b64 s[0:1], -1, 0
	s_lshr_b32 s4, s86, 7
	s_bfe_u32 s23, s86, 0x10006
	v_writelane_b32 v240, s75, 41
	s_cmp_lg_u32 s4, 1
	s_mov_b32 s10, s86
	s_cselect_b64 s[6:7], -1, 0
	v_writelane_b32 v240, s10, 42
	s_bitcmp1_b32 s86, 6
	v_mul_u32_u24_e32 v2, 0x48, v18
	v_writelane_b32 v240, s11, 43
	s_cselect_b64 s[10:11], -1, 0
	v_lshlrev_b32_e32 v2, 1, v2
	v_lshlrev_b32_e32 v3, 5, v24
	s_or_b64 s[6:7], s[6:7], s[10:11]
	s_lshl_b32 s10, s4, 5
	v_add3_u32 v34, 0, v2, v3
	v_writelane_b32 v240, s6, 44
	v_or_b32_e32 v3, s10, v164
	v_add_u32_e32 v2, 0, v153
	s_movk_i32 s3, 0x110
	v_writelane_b32 v240, s7, 45
	v_mad_u64_u32 v[22:23], s[6:7], v3, s3, v[2:3]
	v_lshl_or_b32 v23, s23, 5, v164
	v_mad_u32_u24 v35, v23, s3, v2
	v_lshlrev_b32_e32 v4, 2, v162
	s_add_i32 s3, 0, 0x11800
	v_or_b32_e32 v5, s10, v4
	s_movk_i32 s6, 0x90
	v_mov_b32_e32 v6, s3
	v_lshlrev_b32_e32 v3, 7, v3
	v_mad_u32_u24 v6, v23, s6, v6
	v_sub_u32_e32 v36, v22, v3
	v_mul_u32_u24_e32 v3, 0x880, v24
	v_cmp_gt_u32_e64 s[6:7], v5, v23
	v_or_b32_e32 v38, 1, v1
	v_or_b32_e32 v3, v3, v18
	s_movk_i32 s3, 0x88
	v_writelane_b32 v240, s6, 46
	v_lshl_add_u32 v53, v3, 1, 0
	v_mad_u32_u24 v3, v38, s3, v18
	v_writelane_b32 v240, s7, 47
	v_cmp_lt_u32_e64 s[6:7], v5, v23
	v_lshl_add_u32 v54, v3, 1, 0
	v_or_b32_e32 v3, 2, v5
	v_writelane_b32 v240, s6, 48
	s_ashr_i32 s3, s2, 31
	v_mov_b32_e32 v21, 0
	v_writelane_b32 v240, s7, 49
	v_cmp_gt_u32_e64 s[6:7], v3, v23
	v_or_b32_e32 v3, 3, v5
	v_add_u32_e32 v37, v6, v153
	v_writelane_b32 v240, s6, 50
	v_lshl_add_u32 v73, v5, 1, v6
	s_load_dwordx2 s[8:9], s[74:75], 0x60
	v_writelane_b32 v240, s7, 51
	v_cmp_gt_u32_e64 s[6:7], v3, v23
	v_or_b32_e32 v3, 8, v5
	v_or_b32_e32 v39, 2, v1
	v_writelane_b32 v240, s6, 52
	v_or_b32_e32 v40, 3, v1
	v_or_b32_e32 v41, 4, v1
	v_writelane_b32 v240, s7, 53
	v_cmp_gt_u32_e64 s[6:7], v3, v23
	v_or_b32_e32 v42, 5, v1
	v_or_b32_e32 v43, 6, v1
	v_writelane_b32 v240, s6, 54
	v_or_b32_e32 v44, 7, v1
	v_or_b32_e32 v45, 8, v1
	v_writelane_b32 v240, s7, 55
	v_cmp_lt_u32_e64 s[6:7], v3, v23
	v_or_b32_e32 v3, 10, v5
	v_cmp_gt_u32_e64 s[30:31], v3, v23
	v_writelane_b32 v240, s6, 56
	v_or_b32_e32 v3, 11, v5
	v_cmp_gt_u32_e64 s[34:35], v3, v23
	v_writelane_b32 v240, s7, 57
	s_lshl_b64 s[6:7], s[2:3], 9
	s_add_u32 s6, s90, s6
	v_or_b32_e32 v3, 16, v5
	s_addc_u32 s7, s91, s7
	v_cmp_gt_u32_e64 s[36:37], v3, v23
	v_cmp_lt_u32_e64 s[38:39], v3, v23
	v_or_b32_e32 v3, 18, v5
	v_lshl_add_u64 v[6:7], s[6:7], 0, v[20:21]
	s_mov_b64 s[6:7], 0x6e800000
	v_cmp_gt_u32_e64 s[40:41], v3, v23
	v_or_b32_e32 v3, 19, v5
	v_lshl_add_u64 v[24:25], v[6:7], 0, s[6:7]
	s_lshl_b64 s[6:7], s[2:3], 15
	s_lshl_b32 s3, s23, 14
	v_cmp_gt_u32_e64 s[42:43], v3, v23
	v_or_b32_e32 v3, 24, v5
	s_lshl_b32 s93, s2, 2
	s_lshl_b32 s20, s96, 2
	s_lshl_b32 s21, s2, 7
	s_lshl_b32 s22, s96, 7
	s_or_b32 s3, s6, s3
	s_lshl_b32 s4, s4, 6
	v_cmp_gt_u32_e64 s[44:45], v3, v23
	v_cmp_lt_u32_e64 s[46:47], v3, v23
	v_or_b32_e32 v3, 26, v5
	s_add_u32 s6, s4, s3
	v_cmp_gt_u32_e64 s[18:19], v3, v23
	v_or_b32_e32 v3, 27, v5
	v_lshlrev_b32_e32 v20, 8, v164
	s_addc_u32 s7, 0, s7
	v_cmp_gt_u32_e64 s[50:51], v3, v23
	v_lshl_or_b32 v3, s23, 6, v164
	v_lshl_add_u64 v[6:7], s[6:7], 0, v[20:21]
	v_and_b32_e32 v20, 32, v0
	v_mul_u32_u24_e32 v5, 0x90, v3
	v_or_b32_e32 v3, 32, v3
	v_lshrrev_b32_e32 v20, 2, v20
	v_or_b32_e32 v46, 9, v1
	v_or_b32_e32 v47, 10, v1
	v_or_b32_e32 v48, 11, v1
	v_or_b32_e32 v49, 12, v1
	v_or_b32_e32 v50, 13, v1
	v_or_b32_e32 v51, 14, v1
	v_or_b32_e32 v52, 15, v1
	v_mul_u32_u24_e32 v3, 0x90, v3
	v_or_b32_e32 v6, v6, v20
	s_mov_b32 s5, 0
	v_add_u32_e32 v55, 0x110, v54
	v_add_u32_e32 v56, 0x220, v54
	v_add_u32_e32 v57, 0x330, v54
	v_add_u32_e32 v58, 0x440, v54
	v_add_u32_e32 v59, 0x550, v54
	v_add_u32_e32 v60, 0x660, v54
	v_add_u32_e32 v61, 0x770, v54
	v_add_u32_e32 v62, 0x880, v54
	v_add_u32_e32 v63, 0x990, v54
	v_add_u32_e32 v64, 0xaa0, v54
	v_add_u32_e32 v65, 0xbb0, v54
	v_add_u32_e32 v66, 0xcc0, v54
	v_add_u32_e32 v67, 0xdd0, v54
	v_add_u32_e32 v69, 0xee0, v54
	v_lshlrev_b32_e32 v79, 14, v38
	v_lshlrev_b32_e32 v80, 14, v39
	v_lshlrev_b32_e32 v81, 14, v40
	v_lshlrev_b32_e32 v82, 14, v41
	v_lshlrev_b32_e32 v83, 14, v42
	v_lshlrev_b32_e32 v84, 14, v43
	v_lshlrev_b32_e32 v85, 14, v44
	v_lshlrev_b32_e32 v86, 14, v45
	v_lshlrev_b32_e32 v87, 14, v46
	v_lshlrev_b32_e32 v88, 14, v47
	v_lshlrev_b32_e32 v90, 14, v48
	v_lshlrev_b32_e32 v91, 14, v49
	v_lshlrev_b32_e32 v92, 14, v50
	v_lshlrev_b32_e32 v94, 14, v51
	v_lshlrev_b32_e32 v95, 14, v52
	v_lshl_add_u64 v[26:27], s[90:91], 0, v[6:7]
	s_lshl_b64 s[6:7], s[96:97], 15
	s_mov_b64 s[86:87], 0
	s_movk_i32 s3, 0x2000
	s_mov_b32 s23, 0xc1f00000
	s_mov_b32 s24, 0x800000
	s_mov_b32 s25, 0x3f317217
	s_mov_b32 s26, 0x7f800000
	v_lshlrev_b32_e32 v28, 1, v18
	s_lshl_b32 s94, s10, 1
	v_lshlrev_b32_e32 v30, 1, v4
	v_add_u32_e32 v96, v2, v5
	v_add_u32_e32 v97, v2, v3
	v_mov_b32_e32 v98, 0x41f00000
	v_bfrev_b32_e32 v99, 1
	v_mov_b32_e32 v100, 0x41b17218
	s_mov_b32 s27, s2
	s_and_b32 s4, s21, 0x780
	v_or_b32_e32 v4, s4, v18
	v_lshlrev_b32_e32 v20, 2, v4
	s_waitcnt lgkmcnt(0)
	v_lshl_add_u64 v[2:3], s[8:9], 0, v[20:21]
	v_add_co_u32_e32 v2, vcc, s3, v2
	global_load_dword v253, v20, s[8:9]
	s_nop 0
	v_addc_co_u32_e32 v3, vcc, 0, v3, vcc
	global_load_dword v254, v[2:3], off
	s_nop 0
	s_branch .LBB0_483
